# v10 + attention K/V/Q/block-mean loads with sc1 policy
# baseline (speedup 1.0000x reference)
; __device__ __forceinline__ float bf2f(unsigned short b) { return __uint_as_float(((unsigned)b) << 16); }
; __device__ __forceinline__ void phase_attn(const Params& p, LAS unsigned char* lds, unsigned* queue) {
;     ...
;         const int idx = (int)*tick;
;         if (idx >= 512) break;
;         const int blk = 7 - (idx >> 6), bh = idx & 63, b = bh >> 3, h = bh & 7;
;         const int qpos = blk * 256 + w * 32 + r;
;         const bf16_t* Qp = Qg + ((size_t)bh * 2048 + qpos) * 64 + 8 * hh;
;         bf16x8 qf[4];
; #pragma unroll
;         for (int s = 0; s < 4; ++s) qf[s] = *(const bf16x8*)(Qp + 16 * s);
;         unsigned selmask;
;         if (blk <= 3) selmask = (1u << blk) - 1u;
;         else {
;             float v1 = -3e38f, v2 = -3e38f, v3 = -3e38f; int i1 = 0, i2 = 0, i3 = 0;
; #pragma unroll
;             for (int j = 0; j < 7; ++j) {
;                 if (j < blk) {
;                     const float* ks = KSUM + ((size_t)bh * 8 + j) * 64 + 8 * hh;
;                     float gsum = 0.f;
; #pragma unroll
;                     for (int s = 0; s < 4; ++s) {
;                         const f32x4 k0 = *(const f32x4*)(ks + 16 * s), k1 = *(const f32x4*)(ks + 16 * s + 4);
;                         gsum += bf2f((unsigned short)qf[s][0]) * k0[0] + bf2f((unsigned short)qf[s][1]) * k0[1] + bf2f((unsigned short)qf[s][2]) * k0[2] + bf2f((unsigned short)qf[s][3]) * k0[3]
;                               + bf2f((unsigned short)qf[s][4]) * k1[0] + bf2f((unsigned short)qf[s][5]) * k1[1] + bf2f((unsigned short)qf[s][6]) * k1[2] + bf2f((unsigned short)qf[s][7]) * k1[3];
;                     }
;                     gsum += __shfl_xor(gsum, 32);
;                     if (gsum > v1) { v3 = v2; i3 = i2; v2 = v1; i2 = i1; v1 = gsum; i1 = j; }
;                     else if (gsum > v2) { v3 = v2; i3 = i2; v2 = gsum; i2 = j; }
;                     else if (gsum > v3) { v3 = gsum; i3 = j; }
.LBB0_337:
	s_or_b64 exec, exec, s[4:5]
	s_waitcnt lgkmcnt(0)
	s_barrier
	ds_read_b32 v2, v212
	s_movk_i32 s0, 0x1ff
	s_mov_b64 s[4:5], -1
	s_waitcnt lgkmcnt(0)
	v_cmp_lt_i32_e32 vcc, s0, v2
	v_readfirstlane_b32 s96, v2
	s_cbranch_vccnz .LBB0_332
	s_ashr_i32 s1, s96, 6
	s_sub_i32 s0, 7, s1
	s_and_b32 s97, s96, 63
	s_lshl_b32 s4, s0, 8
	v_add_u32_e32 v187, s4, v199
	s_lshl_b32 s82, s97, 11
	v_add_u32_e32 v2, s82, v187
	v_lshlrev_b64 v[4:5], 7, v[2:3]
	v_lshl_add_u64 v[4:5], v[178:179], 0, v[4:5]
	global_load_dwordx4 v[146:149], v[4:5], off sc1
	global_load_dwordx4 v[150:153], v[4:5], off offset:32 sc1
	global_load_dwordx4 v[154:157], v[4:5], off offset:64 sc1
	global_load_dwordx4 v[158:161], v[4:5], off offset:96 sc1
	s_cmp_gt_i32 s1, 3
	s_mov_b64 s[6:7], -1
	s_cbranch_scc1 .LBB0_380
	v_lshl_add_u64 v[12:13], v[180:181], 0, s[82:83]
	global_load_dwordx4 v[30:33], v[12:13], off sc1
	global_load_dwordx4 v[8:11], v[12:13], off offset:64 sc1
	global_load_dwordx4 v[34:37], v[12:13], off offset:16 sc1
	global_load_dwordx4 v[4:7], v[12:13], off offset:80 sc1
	global_load_dwordx4 v[38:41], v[12:13], off offset:128 sc1
	global_load_dwordx4 v[42:45], v[12:13], off offset:192 sc1
	global_load_dwordx4 v[46:49], v[12:13], off offset:144 sc1
	global_load_dwordx4 v[50:53], v[12:13], off offset:208 sc1
	global_load_dwordx4 v[54:57], v[12:13], off offset:272 sc1
	global_load_dwordx4 v[58:61], v[12:13], off offset:256 sc1
	global_load_dwordx4 v[62:65], v[12:13], off offset:336 sc1
	global_load_dwordx4 v[66:69], v[12:13], off offset:320 sc1
	s_waitcnt vmcnt(14)
	v_and_b32_e32 v19, 0xffff0000, v150
	v_and_b32_e32 v18, 0xffff0000, v146
	v_lshlrev_b32_e32 v15, 16, v150
	v_lshlrev_b32_e32 v14, 16, v146
	v_lshlrev_b32_e32 v17, 16, v151
	v_lshlrev_b32_e32 v16, 16, v147
	v_and_b32_e32 v29, 0xffff0000, v151
	v_and_b32_e32 v28, 0xffff0000, v147
	v_lshlrev_b32_e32 v27, 16, v152
	v_lshlrev_b32_e32 v26, 16, v148
	v_and_b32_e32 v25, 0xffff0000, v152
	v_and_b32_e32 v24, 0xffff0000, v148
	v_lshlrev_b32_e32 v23, 16, v153
	v_lshlrev_b32_e32 v22, 16, v149
	v_and_b32_e32 v21, 0xffff0000, v153
	v_and_b32_e32 v20, 0xffff0000, v149
	v_cmp_lt_i32_e32 vcc, v193, v202
	s_waitcnt vmcnt(11)
	v_mov_b32_e32 v70, v30
	s_waitcnt vmcnt(10)
	v_mov_b32_e32 v71, v8
	v_mov_b32_e32 v8, v31
	v_pk_mul_f32 v[8:9], v[8:9], v[18:19]
	v_mov_b32_e32 v72, v32
	v_mov_b32_e32 v73, v10
	v_pk_fma_f32 v[8:9], v[70:71], v[14:15], v[8:9]
	v_mov_b32_e32 v10, v33
	s_waitcnt vmcnt(9)
	v_mov_b32_e32 v74, v34
	s_waitcnt vmcnt(8)
	v_mov_b32_e32 v75, v4
	v_mov_b32_e32 v4, v35
	s_waitcnt vmcnt(7)
	v_mov_b32_e32 v34, v38
	s_waitcnt vmcnt(6)
	v_mov_b32_e32 v35, v42
	v_mov_b32_e32 v42, v39
	v_and_b32_e32 v33, 0xffff0000, v158
	v_and_b32_e32 v32, 0xffff0000, v154
	v_pk_fma_f32 v[38:39], v[72:73], v[16:17], v[8:9]
	v_mov_b32_e32 v76, v36
	v_mov_b32_e32 v77, v6
	v_mov_b32_e32 v6, v37
	v_mov_b32_e32 v36, v40
	v_mov_b32_e32 v37, v44
	v_mov_b32_e32 v44, v41
	v_lshlrev_b32_e32 v31, 16, v158
	v_lshlrev_b32_e32 v30, 16, v154
	v_pk_fma_f32 v[38:39], v[10:11], v[28:29], v[38:39]
	v_pk_mul_f32 v[40:41], v[42:43], v[32:33]
	v_lshlrev_b32_e32 v9, 16, v159
	v_lshlrev_b32_e32 v8, 16, v155
	v_pk_fma_f32 v[40:41], v[34:35], v[30:31], v[40:41]
	v_pk_fma_f32 v[38:39], v[74:75], v[26:27], v[38:39]
	v_and_b32_e32 v11, 0xffff0000, v159
	v_and_b32_e32 v10, 0xffff0000, v155
	v_pk_fma_f32 v[40:41], v[36:37], v[8:9], v[40:41]
	v_pk_fma_f32 v[4:5], v[4:5], v[24:25], v[38:39]
	s_waitcnt vmcnt(5)
	v_mov_b32_e32 v78, v46
	s_waitcnt vmcnt(4)
	v_mov_b32_e32 v79, v50
	v_mov_b32_e32 v50, v47
	v_mov_b32_e32 v80, v48
	v_mov_b32_e32 v81, v52
	v_mov_b32_e32 v52, v49
	v_lshlrev_b32_e32 v35, 16, v160
	v_lshlrev_b32_e32 v34, 16, v156
	v_pk_fma_f32 v[70:71], v[44:45], v[10:11], v[40:41]
	v_pk_fma_f32 v[4:5], v[76:77], v[22:23], v[4:5]
	global_load_dwordx4 v[38:41], v[12:13], off offset:400 sc1
	global_load_dwordx4 v[42:45], v[12:13], off offset:384 sc1
	global_load_dwordx4 v[46:49], v[12:13], off offset:448 sc1
	v_and_b32_e32 v37, 0xffff0000, v160
	v_pk_fma_f32 v[72:73], v[6:7], v[20:21], v[4:5]
	v_and_b32_e32 v36, 0xffff0000, v156
	v_pk_fma_f32 v[6:7], v[78:79], v[34:35], v[70:71]
	v_lshlrev_b32_e32 v5, 16, v161
	v_lshlrev_b32_e32 v4, 16, v157
	v_pk_fma_f32 v[6:7], v[50:51], v[36:37], v[6:7]
	v_add_f32_e32 v2, 0, v72
	v_pk_fma_f32 v[50:51], v[80:81], v[4:5], v[6:7]
	v_and_b32_e32 v7, 0xffff0000, v161
	v_and_b32_e32 v6, 0xffff0000, v157
	v_pk_fma_f32 v[70:71], v[52:53], v[6:7], v[50:51]
	global_load_dwordx4 v[50:53], v[12:13], off offset:464 sc1
	v_add_f32_e32 v2, v2, v73
	s_waitcnt vmcnt(4)
	v_mov_b32_e32 v73, v66
	v_mov_b32_e32 v66, v59
	v_mov_b32_e32 v72, v58
	v_pk_mul_f32 v[58:59], v[66:67], v[18:19]
	v_mov_b32_e32 v66, v60
	v_pk_fma_f32 v[58:59], v[72:73], v[14:15], v[58:59]
	v_mov_b32_e32 v67, v68
	v_pk_fma_f32 v[58:59], v[66:67], v[16:17], v[58:59]
	v_mov_b32_e32 v68, v61
	v_pk_fma_f32 v[58:59], v[68:69], v[28:29], v[58:59]
	v_mov_b32_e32 v60, v54
	v_mov_b32_e32 v61, v62
	v_pk_fma_f32 v[58:59], v[60:61], v[26:27], v[58:59]
	v_mov_b32_e32 v62, v55
	v_pk_fma_f32 v[54:55], v[62:63], v[24:25], v[58:59]
	v_mov_b32_e32 v58, v56
	v_mov_b32_e32 v59, v64
	v_pk_fma_f32 v[54:55], v[58:59], v[22:23], v[54:55]
	v_mov_b32_e32 v64, v57
	v_pk_fma_f32 v[54:55], v[64:65], v[20:21], v[54:55]
	v_add_f32_e32 v2, v2, v70
	v_add_f32_e32 v54, 0, v54
	v_add_f32_e32 v56, v54, v55
	v_add_f32_e32 v70, v2, v71
	v_cndmask_b32_e32 v2, v192, v193, vcc
	v_lshlrev_b32_e32 v2, 2, v2
	ds_bpermute_b32 v66, v2, v70
	s_waitcnt vmcnt(2)
	v_mov_b32_e32 v54, v42
	s_waitcnt vmcnt(1)
	v_mov_b32_e32 v55, v46
	v_mov_b32_e32 v46, v43
	v_pk_mul_f32 v[42:43], v[46:47], v[32:33]
	v_mov_b32_e32 v46, v44
	v_pk_fma_f32 v[42:43], v[54:55], v[30:31], v[42:43]
	v_mov_b32_e32 v47, v48
	v_pk_fma_f32 v[42:43], v[46:47], v[8:9], v[42:43]
	v_mov_b32_e32 v48, v45
	v_pk_fma_f32 v[42:43], v[48:49], v[10:11], v[42:43]
	v_mov_b32_e32 v44, v38
	s_waitcnt vmcnt(0)
	v_mov_b32_e32 v45, v50
	v_pk_fma_f32 v[42:43], v[44:45], v[34:35], v[42:43]
	v_mov_b32_e32 v50, v39
	v_pk_fma_f32 v[38:39], v[50:51], v[36:37], v[42:43]
	v_mov_b32_e32 v42, v40
	v_mov_b32_e32 v43, v52
	v_pk_fma_f32 v[38:39], v[42:43], v[4:5], v[38:39]
	v_mov_b32_e32 v52, v41
	v_pk_fma_f32 v[38:39], v[52:53], v[6:7], v[38:39]
	v_mov_b32_e32 v44, 0
	v_add_f32_e32 v38, v56, v38
	v_add_f32_e32 v39, v38, v39
	ds_bpermute_b32 v40, v2, v39
	s_waitcnt lgkmcnt(1)
	v_add_f32_e32 v38, v70, v66
	v_max_f32_e32 v38, 0xff61b1e6, v38
	v_mov_b32_e32 v41, 1
	v_mov_b32_e32 v45, v38
	s_waitcnt lgkmcnt(0)
	v_add_f32_e32 v40, v39, v40
	v_cmp_ngt_f32_e32 vcc, v40, v38
	s_and_saveexec_b64 s[6:7], vcc
	s_cbranch_execz .LBB0_343
	s_mov_b32 s5, 0xff61b1e6
	v_cmp_nlt_f32_e32 vcc, s5, v40
	v_mov_b32_e32 v44, 1
	s_and_saveexec_b64 s[8:9], vcc
	v_mov_b32_e32 v44, 0
	v_mov_b32_e32 v40, 0xff61b1e6
	s_or_b64 exec, exec, s[8:9]
	v_mov_b32_e32 v41, 0
	v_mov_b32_e32 v45, v40
	v_mov_b32_e32 v40, v38
; __device__ __forceinline__ float bf2f(unsigned short b) { return __uint_as_float(((unsigned)b) << 16); }
; __device__ __forceinline__ void phase_attn(const Params& p, LAS unsigned char* lds, unsigned* queue) {
;     ...
;                     const float* ks = KSUM + ((size_t)bh * 8 + j) * 64 + 8 * hh;
;                     float gsum = 0.f;
; #pragma unroll
;                     for (int s = 0; s < 4; ++s) {
;                         const f32x4 k0 = *(const f32x4*)(ks + 16 * s), k1 = *(const f32x4*)(ks + 16 * s + 4);
;                         gsum += bf2f((unsigned short)qf[s][0]) * k0[0] + bf2f((unsigned short)qf[s][1]) * k0[1] + bf2f((unsigned short)qf[s][2]) * k0[2] + bf2f((unsigned short)qf[s][3]) * k0[3]
;                               + bf2f((unsigned short)qf[s][4]) * k1[0] + bf2f((unsigned short)qf[s][5]) * k1[1] + bf2f((unsigned short)qf[s][6]) * k1[2] + bf2f((unsigned short)qf[s][7]) * k1[3];
;                     }
;                     gsum += __shfl_xor(gsum, 32);
;                     if (gsum > v1) { v3 = v2; i3 = i2; v2 = v1; i2 = i1; v1 = gsum; i1 = j; }
;                     else if (gsum > v2) { v3 = v2; i3 = i2; v2 = gsum; i2 = j; }
;                     else if (gsum > v3) { v3 = gsum; i3 = j; }
.LBB0_343:
	s_or_b64 exec, exec, s[6:7]
	global_load_dwordx4 v[46:49], v[12:13], off offset:512 sc1
	global_load_dwordx4 v[50:53], v[12:13], off offset:576 sc1
	global_load_dwordx4 v[54:57], v[12:13], off offset:528 sc1
	global_load_dwordx4 v[58:61], v[12:13], off offset:592 sc1
	global_load_dwordx4 v[62:65], v[12:13], off offset:640 sc1
	global_load_dwordx4 v[66:69], v[12:13], off offset:704 sc1
	global_load_dwordx4 v[70:73], v[12:13], off offset:656 sc1
	global_load_dwordx4 v[74:77], v[12:13], off offset:720 sc1
	s_waitcnt vmcnt(7)
	v_mov_b32_e32 v38, v46
	s_waitcnt vmcnt(6)
	v_mov_b32_e32 v39, v50
	v_mov_b32_e32 v50, v47
	v_pk_mul_f32 v[50:51], v[50:51], v[18:19]
	v_mov_b32_e32 v42, v48
	v_mov_b32_e32 v43, v52
	s_waitcnt vmcnt(4)
	v_mov_b32_e32 v47, v58
	v_mov_b32_e32 v58, v55
	s_waitcnt vmcnt(2)
	v_mov_b32_e32 v55, v66
	v_mov_b32_e32 v66, v63
	v_pk_fma_f32 v[38:39], v[38:39], v[14:15], v[50:51]
	v_mov_b32_e32 v52, v49
	v_mov_b32_e32 v46, v54
	v_mov_b32_e32 v54, v62
	v_pk_mul_f32 v[66:67], v[66:67], v[32:33]
	v_pk_fma_f32 v[38:39], v[42:43], v[16:17], v[38:39]
	v_mov_b32_e32 v48, v56
	v_mov_b32_e32 v49, v60
	v_mov_b32_e32 v60, v57
	v_mov_b32_e32 v56, v64
	v_mov_b32_e32 v57, v68
	v_pk_fma_f32 v[50:51], v[54:55], v[30:31], v[66:67]
	v_pk_fma_f32 v[38:39], v[52:53], v[28:29], v[38:39]
	v_mov_b32_e32 v68, v65
	v_pk_fma_f32 v[42:43], v[56:57], v[8:9], v[50:51]
	v_pk_fma_f32 v[38:39], v[46:47], v[26:27], v[38:39]
	s_waitcnt vmcnt(1)
	v_mov_b32_e32 v62, v70
	s_waitcnt vmcnt(0)
	v_mov_b32_e32 v63, v74
	v_pk_fma_f32 v[42:43], v[68:69], v[10:11], v[42:43]
	v_pk_fma_f32 v[38:39], v[58:59], v[24:25], v[38:39]
	v_mov_b32_e32 v74, v71
	v_pk_fma_f32 v[42:43], v[62:63], v[34:35], v[42:43]
	v_pk_fma_f32 v[38:39], v[48:49], v[22:23], v[38:39]
	v_mov_b32_e32 v64, v72
	v_mov_b32_e32 v65, v76
	v_pk_fma_f32 v[42:43], v[74:75], v[36:37], v[42:43]
	v_pk_fma_f32 v[38:39], v[60:61], v[20:21], v[38:39]
	v_mov_b32_e32 v76, v73
	v_pk_fma_f32 v[42:43], v[64:65], v[4:5], v[42:43]
	v_add_f32_e32 v38, 0, v38
	v_pk_fma_f32 v[42:43], v[76:77], v[6:7], v[42:43]
	v_add_f32_e32 v38, v38, v39
	v_add_f32_e32 v38, v38, v42
	v_add_f32_e32 v39, v38, v43
	ds_bpermute_b32 v42, v2, v39
	v_mov_b32_e32 v47, 2
	v_mov_b32_e32 v38, v41
	s_waitcnt lgkmcnt(0)
	v_add_f32_e32 v46, v39, v42
	v_cmp_ngt_f32_e32 vcc, v46, v40
	v_mov_b32_e32 v39, v40
	s_and_saveexec_b64 s[6:7], vcc
	s_cbranch_execz .LBB0_349
	v_cmp_ngt_f32_e32 vcc, v46, v45
	v_mov_b32_e32 v38, 2
	s_and_saveexec_b64 s[8:9], vcc
	s_cbranch_execz .LBB0_348
	v_mov_b32_e32 v38, 0xff61b1e6
	v_cmp_gt_f32_e32 vcc, v46, v38
	v_mov_b32_e32 v39, 0
	s_and_saveexec_b64 s[10:11], vcc
	v_mov_b32_e32 v39, 2
	v_mov_b32_e32 v38, v46
	s_or_b64 exec, exec, s[10:11]
	v_mov_b32_e32 v46, v45
	v_mov_b32_e32 v45, v38
	v_mov_b32_e32 v38, v44
	v_mov_b32_e32 v44, v39

; __device__ __forceinline__ float bf2f(unsigned short b) { return __uint_as_float(((unsigned)b) << 16); }
; __device__ __forceinline__ void phase_attn(const Params& p, LAS unsigned char* lds, unsigned* queue) {
;     ...
;                     const float* ks = KSUM + ((size_t)bh * 8 + j) * 64 + 8 * hh;
;                     float gsum = 0.f;
; #pragma unroll
;                     for (int s = 0; s < 4; ++s) {
;                         const f32x4 k0 = *(const f32x4*)(ks + 16 * s), k1 = *(const f32x4*)(ks + 16 * s + 4);
;                         gsum += bf2f((unsigned short)qf[s][0]) * k0[0] + bf2f((unsigned short)qf[s][1]) * k0[1] + bf2f((unsigned short)qf[s][2]) * k0[2] + bf2f((unsigned short)qf[s][3]) * k0[3]
;                               + bf2f((unsigned short)qf[s][4]) * k1[0] + bf2f((unsigned short)qf[s][5]) * k1[1] + bf2f((unsigned short)qf[s][6]) * k1[2] + bf2f((unsigned short)qf[s][7]) * k1[3];
;                     }
;                     gsum += __shfl_xor(gsum, 32);
;                     if (gsum > v1) { v3 = v2; i3 = i2; v2 = v1; i2 = i1; v1 = gsum; i1 = j; }
;                     else if (gsum > v2) { v3 = v2; i3 = i2; v2 = gsum; i2 = j; }
;                     else if (gsum > v3) { v3 = gsum; i3 = j; }
.LBB0_349:
	s_or_b64 exec, exec, s[6:7]
	global_load_dwordx4 v[40:43], v[12:13], off offset:768 sc1
	global_load_dwordx4 v[48:51], v[12:13], off offset:832 sc1
	global_load_dwordx4 v[52:55], v[12:13], off offset:784 sc1
	global_load_dwordx4 v[56:59], v[12:13], off offset:848 sc1
	global_load_dwordx4 v[60:63], v[12:13], off offset:896 sc1
	global_load_dwordx4 v[64:67], v[12:13], off offset:960 sc1
	global_load_dwordx4 v[68:71], v[12:13], off offset:912 sc1
	global_load_dwordx4 v[72:75], v[12:13], off offset:976 sc1
	s_waitcnt vmcnt(7)
	v_mov_b32_e32 v76, v40
	s_waitcnt vmcnt(6)
	v_mov_b32_e32 v77, v48
	v_mov_b32_e32 v48, v41
	v_pk_mul_f32 v[48:49], v[48:49], v[18:19]
	v_mov_b32_e32 v40, v42
	v_mov_b32_e32 v41, v50
	v_mov_b32_e32 v50, v43
	s_waitcnt vmcnt(4)
	v_mov_b32_e32 v43, v56
	v_mov_b32_e32 v56, v53
	v_mov_b32_e32 v53, v58
	v_mov_b32_e32 v58, v55
	s_waitcnt vmcnt(2)
	v_mov_b32_e32 v55, v64
	v_mov_b32_e32 v64, v61
	v_pk_fma_f32 v[48:49], v[76:77], v[14:15], v[48:49]
	v_mov_b32_e32 v42, v52
	v_mov_b32_e32 v52, v54
	v_mov_b32_e32 v54, v60
	v_pk_mul_f32 v[64:65], v[64:65], v[32:33]
	v_pk_fma_f32 v[40:41], v[40:41], v[16:17], v[48:49]
	v_mov_b32_e32 v60, v62
	v_mov_b32_e32 v61, v66
	v_pk_fma_f32 v[54:55], v[54:55], v[30:31], v[64:65]
	v_pk_fma_f32 v[40:41], v[50:51], v[28:29], v[40:41]
	v_mov_b32_e32 v66, v63
	v_pk_fma_f32 v[48:49], v[60:61], v[8:9], v[54:55]
	v_pk_fma_f32 v[40:41], v[42:43], v[26:27], v[40:41]
	s_waitcnt vmcnt(1)
	v_mov_b32_e32 v62, v68
	s_waitcnt vmcnt(0)
	v_mov_b32_e32 v63, v72
	v_pk_fma_f32 v[48:49], v[66:67], v[10:11], v[48:49]
	v_pk_fma_f32 v[40:41], v[56:57], v[24:25], v[40:41]
	v_mov_b32_e32 v72, v69
	v_pk_fma_f32 v[42:43], v[62:63], v[34:35], v[48:49]
	v_pk_fma_f32 v[40:41], v[52:53], v[22:23], v[40:41]
	v_mov_b32_e32 v68, v70
	v_mov_b32_e32 v69, v74
	v_pk_fma_f32 v[42:43], v[72:73], v[36:37], v[42:43]
	v_pk_fma_f32 v[40:41], v[58:59], v[20:21], v[40:41]
	v_mov_b32_e32 v74, v71
	v_pk_fma_f32 v[42:43], v[68:69], v[4:5], v[42:43]
	v_add_f32_e32 v40, 0, v40
	v_pk_fma_f32 v[42:43], v[74:75], v[6:7], v[42:43]
	v_add_f32_e32 v40, v40, v41
	v_add_f32_e32 v40, v40, v42
	v_add_f32_e32 v42, v40, v43
	ds_bpermute_b32 v43, v2, v42
	v_mov_b32_e32 v41, 3
	v_mov_b32_e32 v40, v47
	s_waitcnt lgkmcnt(0)
	v_add_f32_e32 v42, v42, v43
	v_cmp_ngt_f32_e32 vcc, v42, v46
	v_mov_b32_e32 v43, v46
	s_and_saveexec_b64 s[6:7], vcc
	s_cbranch_execz .LBB0_363
	v_cmp_ngt_f32_e32 vcc, v42, v39
	v_mov_b32_e32 v40, 3
	s_and_saveexec_b64 s[8:9], vcc
	s_cbranch_execz .LBB0_354
	v_cmp_gt_f32_e32 vcc, v42, v45
	s_and_saveexec_b64 s[10:11], vcc
	v_mov_b32_e32 v44, 3
	v_mov_b32_e32 v45, v42
	s_or_b64 exec, exec, s[10:11]
	v_mov_b32_e32 v42, v39
	v_mov_b32_e32 v39, v45
	v_mov_b32_e32 v40, v38
	v_mov_b32_e32 v38, v44

; __device__ __forceinline__ float bf2f(unsigned short b) { return __uint_as_float(((unsigned)b) << 16); }
; __device__ __forceinline__ void phase_attn(const Params& p, LAS unsigned char* lds, unsigned* queue) {
;     ...
;                     const float* ks = KSUM + ((size_t)bh * 8 + j) * 64 + 8 * hh;
;                     float gsum = 0.f;
; #pragma unroll
;                     for (int s = 0; s < 4; ++s) {
;                         const f32x4 k0 = *(const f32x4*)(ks + 16 * s), k1 = *(const f32x4*)(ks + 16 * s + 4);
;                         gsum += bf2f((unsigned short)qf[s][0]) * k0[0] + bf2f((unsigned short)qf[s][1]) * k0[1] + bf2f((unsigned short)qf[s][2]) * k0[2] + bf2f((unsigned short)qf[s][3]) * k0[3]
;                               + bf2f((unsigned short)qf[s][4]) * k1[0] + bf2f((unsigned short)qf[s][5]) * k1[1] + bf2f((unsigned short)qf[s][6]) * k1[2] + bf2f((unsigned short)qf[s][7]) * k1[3];
;                     }
;                     gsum += __shfl_xor(gsum, 32);
;                     if (gsum > v1) { v3 = v2; i3 = i2; v2 = v1; i2 = i1; v1 = gsum; i1 = j; }
;                     else if (gsum > v2) { v3 = v2; i3 = i2; v2 = gsum; i2 = j; }
;                     else if (gsum > v3) { v3 = gsum; i3 = j; }
.LBB0_356:
	global_load_dwordx4 v[44:47], v[12:13], off offset:1280 sc1
	global_load_dwordx4 v[48:51], v[12:13], off offset:1344 sc1
	global_load_dwordx4 v[52:55], v[12:13], off offset:1296 sc1
	global_load_dwordx4 v[56:59], v[12:13], off offset:1360 sc1
	global_load_dwordx4 v[60:63], v[12:13], off offset:1408 sc1
	global_load_dwordx4 v[64:67], v[12:13], off offset:1472 sc1
	global_load_dwordx4 v[68:71], v[12:13], off offset:1424 sc1
	global_load_dwordx4 v[72:75], v[12:13], off offset:1488 sc1
	s_waitcnt vmcnt(7)
	v_mov_b32_e32 v76, v44
	s_waitcnt vmcnt(6)
	v_mov_b32_e32 v77, v48
	v_mov_b32_e32 v48, v45
	v_pk_mul_f32 v[48:49], v[48:49], v[18:19]
	v_mov_b32_e32 v44, v46
	v_mov_b32_e32 v45, v50
	v_mov_b32_e32 v50, v47
	s_waitcnt vmcnt(4)
	v_mov_b32_e32 v47, v56
	v_mov_b32_e32 v56, v53
	v_mov_b32_e32 v53, v58
	v_mov_b32_e32 v58, v55
	s_waitcnt vmcnt(2)
	v_mov_b32_e32 v55, v64
	v_mov_b32_e32 v64, v61
	v_pk_fma_f32 v[48:49], v[76:77], v[14:15], v[48:49]
	v_mov_b32_e32 v46, v52
	v_mov_b32_e32 v52, v54
	v_mov_b32_e32 v54, v60
	v_pk_mul_f32 v[64:65], v[64:65], v[32:33]
	v_pk_fma_f32 v[44:45], v[44:45], v[16:17], v[48:49]
	v_mov_b32_e32 v60, v62
	v_mov_b32_e32 v61, v66
	v_pk_fma_f32 v[54:55], v[54:55], v[30:31], v[64:65]
	v_pk_fma_f32 v[44:45], v[50:51], v[28:29], v[44:45]
	v_mov_b32_e32 v66, v63
	v_pk_fma_f32 v[48:49], v[60:61], v[8:9], v[54:55]
	v_pk_fma_f32 v[44:45], v[46:47], v[26:27], v[44:45]
	s_waitcnt vmcnt(1)
	v_mov_b32_e32 v62, v68
	s_waitcnt vmcnt(0)
	v_mov_b32_e32 v63, v72
	v_pk_fma_f32 v[48:49], v[66:67], v[10:11], v[48:49]
	v_pk_fma_f32 v[44:45], v[56:57], v[24:25], v[44:45]
	v_mov_b32_e32 v72, v69
	v_pk_fma_f32 v[46:47], v[62:63], v[34:35], v[48:49]
	v_pk_fma_f32 v[44:45], v[52:53], v[22:23], v[44:45]
	v_mov_b32_e32 v68, v70
	v_mov_b32_e32 v69, v74
	v_pk_fma_f32 v[46:47], v[72:73], v[36:37], v[46:47]
	v_pk_fma_f32 v[44:45], v[58:59], v[20:21], v[44:45]
	v_mov_b32_e32 v74, v71
	v_pk_fma_f32 v[46:47], v[68:69], v[4:5], v[46:47]
	v_add_f32_e32 v44, 0, v44
	v_pk_fma_f32 v[46:47], v[74:75], v[6:7], v[46:47]
	v_add_f32_e32 v44, v44, v45
	v_add_f32_e32 v44, v44, v46
	v_add_f32_e32 v44, v44, v47
	ds_bpermute_b32 v45, v2, v44
	s_waitcnt lgkmcnt(0)
	v_add_f32_e32 v44, v44, v45
	v_cmp_ngt_f32_e32 vcc, v44, v42
	v_mov_b32_e32 v45, 5
	s_and_saveexec_b64 s[6:7], vcc
	s_cbranch_execz .LBB0_362
	v_cmp_ngt_f32_e32 vcc, v44, v43
	v_mov_b32_e32 v46, 5
	s_and_saveexec_b64 s[8:9], vcc
	s_cbranch_execz .LBB0_361
	v_cmp_gt_f32_e32 vcc, v44, v39
	s_and_saveexec_b64 s[10:11], vcc
	v_mov_b32_e32 v38, 5
	v_mov_b32_e32 v39, v44
	s_or_b64 exec, exec, s[10:11]
	v_mov_b32_e32 v44, v43
	v_mov_b32_e32 v43, v39
	v_mov_b32_e32 v46, v40
	v_mov_b32_e32 v40, v38

; __device__ __forceinline__ float bf2f(unsigned short b) { return __uint_as_float(((unsigned)b) << 16); }
; __device__ __forceinline__ void phase_attn(const Params& p, LAS unsigned char* lds, unsigned* queue) {
;     ...
;                     const float* ks = KSUM + ((size_t)bh * 8 + j) * 64 + 8 * hh;
;                     float gsum = 0.f;
; #pragma unroll
;                     for (int s = 0; s < 4; ++s) {
;                         const f32x4 k0 = *(const f32x4*)(ks + 16 * s), k1 = *(const f32x4*)(ks + 16 * s + 4);
;                         gsum += bf2f((unsigned short)qf[s][0]) * k0[0] + bf2f((unsigned short)qf[s][1]) * k0[1] + bf2f((unsigned short)qf[s][2]) * k0[2] + bf2f((unsigned short)qf[s][3]) * k0[3]
;                               + bf2f((unsigned short)qf[s][4]) * k1[0] + bf2f((unsigned short)qf[s][5]) * k1[1] + bf2f((unsigned short)qf[s][6]) * k1[2] + bf2f((unsigned short)qf[s][7]) * k1[3];
;                     }
;                     gsum += __shfl_xor(gsum, 32);
;                     if (gsum > v1) { v3 = v2; i3 = i2; v2 = v1; i2 = i1; v1 = gsum; i1 = j; }
;                     else if (gsum > v2) { v3 = v2; i3 = i2; v2 = gsum; i2 = j; }
;                     else if (gsum > v3) { v3 = gsum; i3 = j; }
.LBB0_364:
	global_load_dwordx4 v[44:47], v[12:13], off offset:1024 sc1
	global_load_dwordx4 v[48:51], v[12:13], off offset:1088 sc1
	global_load_dwordx4 v[52:55], v[12:13], off offset:1040 sc1
	global_load_dwordx4 v[56:59], v[12:13], off offset:1104 sc1
	global_load_dwordx4 v[60:63], v[12:13], off offset:1152 sc1
	global_load_dwordx4 v[64:67], v[12:13], off offset:1216 sc1
	global_load_dwordx4 v[68:71], v[12:13], off offset:1168 sc1
	global_load_dwordx4 v[72:75], v[12:13], off offset:1232 sc1
	s_waitcnt vmcnt(7)
	v_mov_b32_e32 v76, v44
	s_waitcnt vmcnt(6)
	v_mov_b32_e32 v77, v48
	v_mov_b32_e32 v48, v45
	v_pk_mul_f32 v[48:49], v[48:49], v[18:19]
	v_mov_b32_e32 v44, v46
	v_mov_b32_e32 v45, v50
	v_mov_b32_e32 v50, v47
	s_waitcnt vmcnt(4)
	v_mov_b32_e32 v47, v56
	v_mov_b32_e32 v56, v53
	v_mov_b32_e32 v53, v58
	v_mov_b32_e32 v58, v55
	s_waitcnt vmcnt(2)
	v_mov_b32_e32 v55, v64
	v_mov_b32_e32 v64, v61
	v_pk_fma_f32 v[48:49], v[76:77], v[14:15], v[48:49]
	v_mov_b32_e32 v46, v52
	v_mov_b32_e32 v52, v54
	v_mov_b32_e32 v54, v60
	v_pk_mul_f32 v[64:65], v[64:65], v[32:33]
	v_pk_fma_f32 v[44:45], v[44:45], v[16:17], v[48:49]
	v_mov_b32_e32 v60, v62
	v_mov_b32_e32 v61, v66
	v_pk_fma_f32 v[54:55], v[54:55], v[30:31], v[64:65]
	v_pk_fma_f32 v[44:45], v[50:51], v[28:29], v[44:45]
	v_mov_b32_e32 v66, v63
	v_pk_fma_f32 v[48:49], v[60:61], v[8:9], v[54:55]
	v_pk_fma_f32 v[44:45], v[46:47], v[26:27], v[44:45]
	s_waitcnt vmcnt(1)
	v_mov_b32_e32 v62, v68
	s_waitcnt vmcnt(0)
	v_mov_b32_e32 v63, v72
	v_pk_fma_f32 v[48:49], v[66:67], v[10:11], v[48:49]
	v_pk_fma_f32 v[44:45], v[56:57], v[24:25], v[44:45]
	v_mov_b32_e32 v72, v69
	v_pk_fma_f32 v[46:47], v[62:63], v[34:35], v[48:49]
	v_pk_fma_f32 v[44:45], v[52:53], v[22:23], v[44:45]
	v_mov_b32_e32 v68, v70
	v_mov_b32_e32 v69, v74
	v_pk_fma_f32 v[46:47], v[72:73], v[36:37], v[46:47]
	v_pk_fma_f32 v[44:45], v[58:59], v[20:21], v[44:45]
	v_mov_b32_e32 v74, v71
	v_pk_fma_f32 v[46:47], v[68:69], v[4:5], v[46:47]
	v_add_f32_e32 v44, 0, v44
	v_pk_fma_f32 v[46:47], v[74:75], v[6:7], v[46:47]
	v_add_f32_e32 v44, v44, v45
	v_add_f32_e32 v44, v44, v46
	v_add_f32_e32 v44, v44, v47
	ds_bpermute_b32 v45, v2, v44
	s_waitcnt lgkmcnt(0)
	v_add_f32_e32 v44, v44, v45
	v_cmp_ngt_f32_e32 vcc, v44, v42
	v_mov_b32_e32 v45, 4
	s_and_saveexec_b64 s[6:7], vcc
	s_cbranch_execz .LBB0_370
	v_cmp_ngt_f32_e32 vcc, v44, v43
	v_mov_b32_e32 v46, 4
	s_and_saveexec_b64 s[8:9], vcc
	s_cbranch_execz .LBB0_369
	v_cmp_gt_f32_e32 vcc, v44, v39
	s_and_saveexec_b64 s[10:11], vcc
	v_mov_b32_e32 v38, 4
	v_mov_b32_e32 v39, v44
	s_or_b64 exec, exec, s[10:11]
	v_mov_b32_e32 v44, v43
	v_mov_b32_e32 v43, v39
	v_mov_b32_e32 v46, v40
	v_mov_b32_e32 v40, v38

; __device__ __forceinline__ float bf2f(unsigned short b) { return __uint_as_float(((unsigned)b) << 16); }
; __device__ __forceinline__ void phase_attn(const Params& p, LAS unsigned char* lds, unsigned* queue) {
;     ...
;                     const float* ks = KSUM + ((size_t)bh * 8 + j) * 64 + 8 * hh;
;                     float gsum = 0.f;
; #pragma unroll
;                     for (int s = 0; s < 4; ++s) {
;                         const f32x4 k0 = *(const f32x4*)(ks + 16 * s), k1 = *(const f32x4*)(ks + 16 * s + 4);
;                         gsum += bf2f((unsigned short)qf[s][0]) * k0[0] + bf2f((unsigned short)qf[s][1]) * k0[1] + bf2f((unsigned short)qf[s][2]) * k0[2] + bf2f((unsigned short)qf[s][3]) * k0[3]
;                               + bf2f((unsigned short)qf[s][4]) * k1[0] + bf2f((unsigned short)qf[s][5]) * k1[1] + bf2f((unsigned short)qf[s][6]) * k1[2] + bf2f((unsigned short)qf[s][7]) * k1[3];
;                     }
;                     gsum += __shfl_xor(gsum, 32);
;                     if (gsum > v1) { v3 = v2; i3 = i2; v2 = v1; i2 = i1; v1 = gsum; i1 = j; }
;                     else if (gsum > v2) { v3 = v2; i3 = i2; v2 = gsum; i2 = j; }
;                     else if (gsum > v3) { v3 = gsum; i3 = j; }
.LBB0_372:
	global_load_dwordx4 v[44:47], v[12:13], off offset:1536 sc1
	global_load_dwordx4 v[48:51], v[12:13], off offset:1600 sc1
	global_load_dwordx4 v[52:55], v[12:13], off offset:1552 sc1
	global_load_dwordx4 v[56:59], v[12:13], off offset:1616 sc1
	global_load_dwordx4 v[60:63], v[12:13], off offset:1664 sc1
	global_load_dwordx4 v[64:67], v[12:13], off offset:1728 sc1
	global_load_dwordx4 v[68:71], v[12:13], off offset:1680 sc1
	global_load_dwordx4 v[72:75], v[12:13], off offset:1744 sc1
	s_waitcnt vmcnt(7)
	v_mov_b32_e32 v12, v44
	s_waitcnt vmcnt(6)
	v_mov_b32_e32 v13, v48
	v_mov_b32_e32 v48, v45
	v_mov_b32_e32 v45, v50
	v_mov_b32_e32 v50, v47
	s_waitcnt vmcnt(4)
	v_mov_b32_e32 v47, v56
	v_mov_b32_e32 v56, v53
	v_mov_b32_e32 v53, v58
	v_mov_b32_e32 v58, v55
	s_waitcnt vmcnt(2)
	v_mov_b32_e32 v55, v64
	v_mov_b32_e32 v64, v61
	v_pk_mul_f32 v[18:19], v[48:49], v[18:19]
	v_mov_b32_e32 v44, v46
	v_mov_b32_e32 v46, v52
	v_mov_b32_e32 v52, v54
	v_mov_b32_e32 v54, v60
	v_pk_mul_f32 v[32:33], v[64:65], v[32:33]
	v_pk_fma_f32 v[12:13], v[12:13], v[14:15], v[18:19]
	v_mov_b32_e32 v60, v62
	v_mov_b32_e32 v61, v66
	v_pk_fma_f32 v[14:15], v[54:55], v[30:31], v[32:33]
	v_pk_fma_f32 v[12:13], v[44:45], v[16:17], v[12:13]
	v_mov_b32_e32 v66, v63
	v_pk_fma_f32 v[8:9], v[60:61], v[8:9], v[14:15]
	v_pk_fma_f32 v[12:13], v[50:51], v[28:29], v[12:13]
	s_waitcnt vmcnt(1)
	v_mov_b32_e32 v62, v68
	s_waitcnt vmcnt(0)
	v_mov_b32_e32 v63, v72
	v_pk_fma_f32 v[8:9], v[66:67], v[10:11], v[8:9]
	v_pk_fma_f32 v[10:11], v[46:47], v[26:27], v[12:13]
	v_mov_b32_e32 v72, v69
	v_pk_fma_f32 v[8:9], v[62:63], v[34:35], v[8:9]
	v_pk_fma_f32 v[10:11], v[56:57], v[24:25], v[10:11]
	v_mov_b32_e32 v68, v70
	v_mov_b32_e32 v69, v74
	v_pk_fma_f32 v[8:9], v[72:73], v[36:37], v[8:9]
	v_pk_fma_f32 v[10:11], v[52:53], v[22:23], v[10:11]
	v_mov_b32_e32 v74, v71
	v_pk_fma_f32 v[4:5], v[68:69], v[4:5], v[8:9]
	v_pk_fma_f32 v[8:9], v[58:59], v[20:21], v[10:11]
	v_pk_fma_f32 v[4:5], v[74:75], v[6:7], v[4:5]
	v_add_f32_e32 v6, 0, v8
	v_add_f32_e32 v6, v6, v9
	v_add_f32_e32 v4, v6, v4
	v_add_f32_e32 v4, v4, v5
	ds_bpermute_b32 v2, v2, v4
	s_waitcnt lgkmcnt(0)
	v_add_f32_e32 v2, v4, v2
	v_cmp_ngt_f32_e32 vcc, v2, v42
	v_mov_b32_e32 v4, 6
	s_and_saveexec_b64 s[6:7], vcc
	s_cbranch_execz .LBB0_378
	v_cmp_ngt_f32_e32 vcc, v2, v43
	v_mov_b32_e32 v5, 6
	s_and_saveexec_b64 s[8:9], vcc
	s_cbranch_execz .LBB0_377
	v_cmp_gt_f32_e32 vcc, v2, v39
	s_and_saveexec_b64 s[10:11], vcc
	v_mov_b32_e32 v38, 6
	s_or_b64 exec, exec, s[10:11]
	v_mov_b32_e32 v5, v40
	v_mov_b32_e32 v40, v38

; #define LAS __attribute__((address_space(3)))
; template <bool DIAG>
; __device__ __forceinline__ void attn_tile(LAS unsigned char* B, unsigned kf_off, unsigned vf_off, const bf16x8 (&qf)[4], f32x16& O0, f32x16& O1, float& mrun, float& lrun,
;                                           bool on, int kpos0, int qpos, int hh) {
;     ...
;         for (int i = 0; i < 16; ++i) {
;             const int key = kpos0 + (i & 7) + 8 * hh + 16 * (i >> 3);
;             if (key > qpos) st0[i] = -1e30f;
;             if (key + 32 > qpos) st1[i] = -1e30f;
; __device__ __forceinline__ void phase_attn(const Params& p, LAS unsigned char* lds, unsigned* queue) {
;     ...
;         const int ntile = 4 + 4 * blk;
;         const bf16_t* Kst = Kg + ((size_t)bh * 2048 + srow) * 64 + sch * 8;
;         const bf16_t* Vst = VTg + ((size_t)bh * 64 + srow) * 2048 + sch * 8;
;         u32x4 kreg[2], vreg[2];
; #pragma unroll
;         for (int q = 0; q < 2; ++q) { const int kp = blk * 256 + 64 * q; kreg[q] = *(const u32x4*)(Kst + (size_t)kp * 64); vreg[q] = *(const u32x4*)(Vst + kp); }
; #pragma unroll
;         for (int q = 0; q < 2; ++q) { *(LAS u32x4*)(lds + q * BUFB + st_off) = kreg[q]; *(LAS u32x4*)(lds + q * BUFB + TILEB + st_off) = vreg[q]; }
;         __syncthreads();
;         for (int n = 0; n < ntile; n += 2) {
;             if (n + 2 < ntile) {
; #pragma unroll
;                 for (int q = 0; q < 2; ++q) { const int m = n + 2 + q; const int kp = m < 4 ? blk * 256 + 64 * m : ((m - 4) >> 2) * 256 + 64 * ((m - 4) & 3);
;                     kreg[q] = *(const u32x4*)(Kst + (size_t)kp * 64); vreg[q] = *(const u32x4*)(Vst + kp); }
.LBB0_382:
	v_or_b32_e32 v2, s82, v200
	v_lshlrev_b32_e32 v2, 7, v2
	s_lshl_b32 s82, s97, 18
	s_mov_b32 s5, s83
	v_lshl_add_u64 v[188:189], v[182:183], 0, v[2:3]
	v_lshl_add_u64 v[190:191], v[184:185], 0, s[82:83]
	s_lshl_b64 s[6:7], s[4:5], 7
	s_or_b32 s82, s4, 64
	v_lshl_add_u64 v[4:5], v[188:189], 0, s[6:7]
	s_lshl_b64 s[6:7], s[82:83], 7
	v_lshl_add_u64 v[6:7], s[4:5], 1, v[190:191]
	global_load_dwordx4 v[162:165], v[4:5], off sc1
	global_load_dwordx4 v[166:169], v[6:7], off sc1
	v_lshl_add_u64 v[4:5], v[188:189], 0, s[6:7]
	global_load_dwordx4 v[170:173], v[4:5], off sc1
	global_load_dwordx4 v[174:177], v[6:7], off offset:128 sc1
	v_or_b32_e32 v2, s4, v203
	v_add_u32_e32 v2, s88, v2
	v_or_b32_e32 v4, 32, v2
	v_or_b32_e32 v16, 7, v2
	v_or_b32_e32 v17, 39, v2
	v_cmp_gt_i32_e64 s[8:9], v4, v187
	v_or_b32_e32 v4, 54, v2
	s_or_b32 s94, s4, 0x80
	s_or_b32 s95, s4, 0xc0
	v_cmp_gt_i32_e64 s[4:5], v2, v187
	v_cmp_lt_i32_e64 s[6:7], v2, v187
	v_or_b32_e32 v5, 33, v2
	v_or_b32_e32 v6, 2, v2
	v_or_b32_e32 v7, 34, v2
	v_or_b32_e32 v8, 3, v2
	v_or_b32_e32 v9, 35, v2
	v_or_b32_e32 v10, 4, v2
	v_or_b32_e32 v11, 36, v2
	v_or_b32_e32 v12, 5, v2
	v_or_b32_e32 v13, 37, v2
	v_or_b32_e32 v14, 6, v2
	v_or_b32_e32 v15, 38, v2
	v_or_b32_e32 v18, 16, v2
	v_or_b32_e32 v19, 48, v2
	v_or_b32_e32 v20, 17, v2
	v_or_b32_e32 v21, 49, v2
	v_or_b32_e32 v22, 18, v2
	v_or_b32_e32 v23, 50, v2
	v_or_b32_e32 v24, 19, v2
	v_or_b32_e32 v25, 51, v2
	v_or_b32_e32 v26, 20, v2
	v_or_b32_e32 v27, 52, v2
	v_or_b32_e32 v28, 21, v2
	v_or_b32_e32 v29, 53, v2
	v_or_b32_e32 v30, 22, v2
	v_cmp_gt_i32_e64 s[34:35], v16, v187
	v_cmp_gt_i32_e64 s[36:37], v17, v187
	v_cmp_gt_i32_e64 s[64:65], v4, v187
	v_or_b32_e32 v4, 23, v2
	v_or_b32_e32 v2, 55, v2
	v_mov_b32_e32 v16, v3
	v_mov_b32_e32 v17, v3
	s_lshl_b32 s33, s0, 2
	v_cmp_gt_i32_e64 s[10:11], v5, v187
	v_cmp_gt_i32_e64 s[12:13], v6, v187
	v_cmp_gt_i32_e64 s[14:15], v7, v187
	v_cmp_gt_i32_e64 s[16:17], v8, v187
	v_cmp_gt_i32_e64 s[18:19], v9, v187
	v_cmp_gt_i32_e64 s[20:21], v10, v187
	v_cmp_gt_i32_e64 s[22:23], v11, v187
	v_cmp_gt_i32_e64 s[24:25], v12, v187
	v_cmp_gt_i32_e64 s[26:27], v13, v187
	v_cmp_gt_i32_e64 s[28:29], v14, v187
	v_cmp_gt_i32_e64 s[30:31], v15, v187
	v_cmp_gt_i32_e64 s[38:39], v18, v187
	v_cmp_gt_i32_e64 s[40:41], v19, v187
	v_cmp_gt_i32_e64 s[42:43], v20, v187
	v_cmp_gt_i32_e64 s[44:45], v21, v187
	v_cmp_gt_i32_e64 s[46:47], v22, v187
	v_cmp_gt_i32_e64 s[48:49], v23, v187
	v_cmp_gt_i32_e64 s[50:51], v24, v187
	v_cmp_gt_i32_e64 s[52:53], v25, v187
	v_cmp_gt_i32_e64 s[54:55], v26, v187
	v_cmp_gt_i32_e64 s[56:57], v27, v187
	v_cmp_gt_i32_e64 s[58:59], v28, v187
	v_cmp_gt_i32_e64 s[60:61], v29, v187
	v_cmp_gt_i32_e64 s[62:63], v30, v187
	v_cmp_gt_i32_e64 s[66:67], v4, v187
	v_cmp_gt_i32_e64 s[68:69], v2, v187
	v_mov_b32_e32 v2, v3
	v_mov_b32_e32 v4, v3
	v_mov_b32_e32 v5, v3
	v_mov_b32_e32 v6, v3
	v_mov_b32_e32 v7, v3
	v_mov_b32_e32 v8, v3
	v_mov_b32_e32 v9, v3
	v_mov_b32_e32 v10, v3
	v_mov_b32_e32 v11, v3
	v_mov_b32_e32 v12, v3
	v_mov_b32_e32 v13, v3
	v_mov_b32_e32 v14, v3
	v_mov_b32_e32 v15, v3
	v_mov_b64_e32 v[32:33], v[16:17]
	v_mov_b64_e32 v[48:49], v[16:17]
	s_add_i32 s33, s33, 4
	s_mov_b32 s78, 0
	v_mov_b32_e32 v214, 0
	s_mov_b32 s79, 0x7fffff80
	s_mov_b32 s0, 0
	v_mov_b64_e32 v[30:31], v[14:15]
	v_mov_b64_e32 v[28:29], v[12:13]
	v_mov_b64_e32 v[26:27], v[10:11]
	v_mov_b64_e32 v[24:25], v[8:9]
	v_mov_b64_e32 v[22:23], v[6:7]
	v_mov_b64_e32 v[20:21], v[4:5]
	v_mov_b64_e32 v[18:19], v[2:3]
	v_mov_b64_e32 v[46:47], v[14:15]
	v_mov_b64_e32 v[44:45], v[12:13]
	v_mov_b64_e32 v[42:43], v[10:11]
	v_mov_b64_e32 v[40:41], v[8:9]
	v_mov_b64_e32 v[38:39], v[6:7]
	v_mov_b64_e32 v[36:37], v[4:5]
	v_mov_b64_e32 v[34:35], v[2:3]
	v_mov_b32_e32 v2, 0
	s_waitcnt vmcnt(3)
	ds_write_b128 v204, v[162:165]
	s_waitcnt vmcnt(2)
	ds_write_b128 v204, v[166:169] offset:9216
	s_waitcnt vmcnt(1)
	ds_write_b128 v204, v[170:173] offset:18432
	s_waitcnt vmcnt(0)
	ds_write_b128 v204, v[174:177] offset:27648
	s_waitcnt lgkmcnt(0)
	s_barrier
.LBB0_383:
	s_add_i32 s80, s0, 2
	s_cmp_lt_u32 s80, s33
	s_cselect_b64 s[86:87], -1, 0
	s_cmp_ge_u32 s80, s33
	s_cselect_b64 s[84:85], -1, 0
	s_and_b64 vcc, exec, s[84:85]
	s_cbranch_vccnz .Lz_prefetch
	s_add_i32 s1, s79, 0x80000100
	s_and_b32 s70, s79, 0x7fffff00
	s_and_b32 s1, s1, 0x80
	s_or_b32 s1, s70, s1
	s_or_b32 s70, s1, 64
	s_cmp_eq_u32 s0, 0
	s_cselect_b32 s82, s94, s1
	s_cselect_b32 s70, s95, s70
	s_lshl_b64 vcc, s[82:83], 7
	s_mov_b32 s71, s83
	v_lshl_add_u64 v[4:5], v[188:189], 0, vcc
	s_lshl_b64 vcc, s[70:71], 7
	v_lshl_add_u64 v[6:7], s[82:83], 1, v[190:191]
	global_load_dwordx4 v[162:165], v[4:5], off sc1
	global_load_dwordx4 v[166:169], v[6:7], off sc1
	v_lshl_add_u64 v[4:5], v[188:189], 0, vcc
	v_lshl_add_u64 v[6:7], s[70:71], 1, v[190:191]
	global_load_dwordx4 v[170:173], v[4:5], off sc1
	global_load_dwordx4 v[174:177], v[6:7], off sc1
